# t8 + CUs>=128 run their GQA unit before the HBM-bound mix step (other half keeps mix first) so mix streams with half the CUs competing
# speedup vs baseline: 1.0000x; 1.0000x over previous
; #define LAS __attribute__((address_space(3)))
; __global__ void __launch_bounds__(512) mega(Args a) {
;   extern __shared__ __attribute__((aligned(16))) char shm[];
;   LAS unsigned char* lds = (LAS unsigned char*)shm;
;   cg::grid_group grid = cg::this_grid();
;   volatile LAS unsigned* xst = (volatile LAS unsigned*)(lds + 128 * 1024);
;   if (threadIdx.x == 0) { xst[0] = 0u; xst[1] = 0u; xst[2] = 0u; xst[3] = 0u; }
;   __syncthreads();
;   const XcdBarrier xb = xcd_barrier_post((unsigned*)(a.ws + WS_BAR), xst);
_Z4mega4Args:
	v_writelane_b32 v250, 0, 29
	v_writelane_b32 v250, 0, 30
	s_load_dwordx8 s[72:79], s[0:1], 0x60
	s_load_dwordx8 s[4:11], s[0:1], 0x40
	s_load_dword s16, s[0:1], 0x80
	s_mov_b32 s68, s2
	v_and_b32_e32 v1, 0x3ff, v0
	s_waitcnt lgkmcnt(0)
	v_writelane_b32 v252, s4, 0
	s_nop 1
	v_writelane_b32 v252, s5, 1
	v_writelane_b32 v252, s6, 2
	v_writelane_b32 v252, s7, 3
	v_writelane_b32 v252, s8, 4
	v_writelane_b32 v252, s9, 5
	v_writelane_b32 v252, s10, 6
	v_writelane_b32 v252, s11, 7
	s_add_u32 s4, s0, 0x78
	s_addc_u32 s5, s1, 0
	v_cmp_eq_u32_e64 s[6:7], 0, v1
	s_mov_b64 s[2:3], exec
	s_nop 0
	v_writelane_b32 v252, s6, 8
	s_nop 1
	v_writelane_b32 v252, s7, 9
	s_and_b64 s[6:7], s[2:3], s[6:7]
	s_mov_b64 exec, s[6:7]
	s_cbranch_execz .LBB0_2
	s_add_i32 s6, 0, 0x20000
	v_mov_b32_e32 v2, 0
	v_mov_b32_e32 v3, s6
	s_add_i32 s6, 0, 0x20004
	ds_write_b32 v3, v2
	v_mov_b32_e32 v3, s6
	s_add_i32 s6, 0, 0x20008
	ds_write_b32 v3, v2
	v_mov_b32_e32 v3, s6
	s_add_i32 s6, 0, 0x2000c
	ds_write_b32 v3, v2
	v_mov_b32_e32 v3, s6
	ds_write_b32 v3, v2

; __device__ __forceinline__ unsigned cvt_pk_bf16(float lo, float hi) { f32x2_t v = {lo, hi}; bf16x2_t r = __builtin_convertvector(v, bf16x2_t); return __builtin_bit_cast(unsigned, r); }
; __device__ __forceinline__ float bf_lo(unsigned w) { return __uint_as_float(w << 16); }
; __device__ __forceinline__ float bf_hi(unsigned w) { return __uint_as_float(w & 0xffff0000u); }
; __global__ void __launch_bounds__(512) mega(Args a) {
;     ...
;     } else if ((PHMASK & 8) && sub == 2) {
;       PH_LOCALS
;       {
;         const int hg = lane >> 4, e8 = (lane & 15) * 8;
;         struct MixIn { float l0, l1, l2; u32x4 o0, o1, o2, z; };
;         auto mix_load = [&](const int tok) { MixIn m;
;           m.l0 = LSE[((size_t)0 * MT + tok) * 4 + hg]; m.l1 = LSE[((size_t)1 * MT + tok) * 4 + hg]; m.l2 = LSE[((size_t)2 * MT + tok) * 4 + hg];
;           m.o0 = __builtin_nontemporal_load((const u32x4*)(OC + ((size_t)0 * MT + tok) * 512 + hg * 128 + e8)); m.o1 = __builtin_nontemporal_load((const u32x4*)(OC + ((size_t)1 * MT + tok) * 512 + hg * 128 + e8));
;           m.o2 = __builtin_nontemporal_load((const u32x4*)(OC + ((size_t)2 * MT + tok) * 512 + hg * 128 + e8)); m.z = *(const u32x4*)(PROJ + (size_t)tok * NIN + C_ZC + hg * 128 + e8); return m; };
;         auto mix_item = [&](const int tok, const MixIn& m) {
;           const float mx = fmaxf(m.l0, fmaxf(m.l1, m.l2)), e0 = __expf(m.l0 - mx), e1 = __expf(m.l1 - mx), e2 = __expf(m.l2 - mx), inv = 1.f / (e0 + e1 + e2);
;           const float w0 = e0 * inv, w1 = e1 * inv, w2 = e2 * inv;
;           u32x4 w;
; #pragma unroll
;           for (int q = 0; q < 4; ++q) { const float lo = (w0 * bf_lo(m.o0[q]) + w1 * bf_lo(m.o1[q]) + w2 * bf_lo(m.o2[q])) * bf_lo(m.z[q]), hi_ = (w0 * bf_hi(m.o0[q]) + w1 * bf_hi(m.o1[q]) + w2 * bf_hi(m.o2[q])) * bf_hi(m.z[q]); w[q] = cvt_pk_bf16(lo, hi_); }
;           *(u32x4*)(Y + (size_t)tok * YW + 2048 + hg * 128 + e8) = w; };
;         int tok0 = gw;
;         for (; tok0 + 3 * NGW < MT; tok0 += 4 * NGW) {
;           const MixIn m0 = mix_load(tok0), m1 = mix_load(tok0 + NGW), m2 = mix_load(tok0 + 2 * NGW), m3 = mix_load(tok0 + 3 * NGW);
;           mix_item(tok0, m0); mix_item(tok0 + NGW, m1); mix_item(tok0 + 2 * NGW, m2); mix_item(tok0 + 3 * NGW, m3);
.LBB0_188:
	v_readlane_b32 s0, v250, 29
	s_cmp_lg_u32 s0, 0
	s_cbranch_scc1 .Lmx_go
	s_cmp_lt_u32 s68, 0x80
	s_cbranch_scc1 .Lmx_go
	v_writelane_b32 v250, 2, 29
.Lmx_go:
	v_mov_b32_e32 v177, v225
	s_mov_b32 s56, s78
	s_mov_b32 s57, s68
	s_lshl_b32 s10, s56, 3
	s_mov_b32 s28, s29
	s_add_u32 s0, s74, s28
	v_ashrrev_i32_e32 v0, 6, v177
	s_addc_u32 s1, s75, 0
	v_lshl_add_u32 v64, s57, 3, v0
	s_add_u32 s8, s0, 0x1a000000
	s_mul_i32 s2, s56, 24
	s_addc_u32 s9, s1, 0
	v_add_u32_e32 v0, s2, v64
	s_movk_i32 s3, 0x4000
	s_add_u32 s38, s0, 0x3d000000
	v_bfe_u32 v94, v177, 4, 2
	v_cmp_gt_i32_e32 vcc, s3, v0
	v_lshlrev_b32_e32 v0, 4, v177
	s_addc_u32 s39, s1, 0
	v_lshlrev_b32_e32 v66, 8, v94
	v_and_b32_e32 v95, 0xf0, v0
	v_readlane_b32 s30, v250, 29
	s_cmp_eq_u32 s30, 2
	s_cbranch_scc0 .Lmx_a
	s_mov_b64 vcc, 0
.Lmx_a:
	s_and_saveexec_b64 s[30:31], vcc
	s_cbranch_execz .LBB0_192
	v_lshlrev_b32_e32 v0, 3, v177
	v_and_b32_e32 v0, 0x78, v0
	v_lshlrev_b32_e32 v192, 2, v94
	v_mov_b32_e32 v67, v193
	v_lshl_add_u64 v[2:3], s[0:1], 0, v[192:193]
	s_mov_b64 s[16:17], 0x48000000
	v_lshl_add_u64 v[4:5], s[0:1], 0, v[66:67]
	v_lshlrev_b32_e32 v6, 1, v0
	v_mov_b32_e32 v7, v193
	v_lshl_add_u64 v[68:69], v[2:3], 0, s[16:17]
	v_lshl_add_u64 v[4:5], v[4:5], 0, v[6:7]
	s_mov_b64 s[16:17], 0x45000000
	v_lshl_add_u64 v[70:71], v[4:5], 0, s[16:17]
	v_add_u32_e32 v4, s10, v64
	s_movk_i32 s15, 0x1400
	v_mad_i64_i32 v[6:7], s[16:17], v4, s15, 0
	v_readlane_b32 s20, v251, 0
	v_or3_b32 v6, v6, v66, v95
	v_readlane_b32 s21, v251, 1
	v_readlane_b32 s22, v251, 2
	v_ashrrev_i32_e32 v5, 31, v4
	v_lshl_add_u64 v[72:73], s[20:21], 0, v[6:7]
	v_mad_i64_i32 v[6:7], s[16:17], v4, s14, 0
	v_or3_b32 v6, v6, v66, v95
	v_readlane_b32 s23, v251, 3
	v_ashrrev_i32_e32 v65, 31, v64
	s_lshl_b32 s36, s56, 5
	v_lshl_add_u64 v[74:75], s[22:23], 0, v[6:7]
	v_lshlrev_b64 v[6:7], 10, v[4:5]
	v_lshlrev_b64 v[4:5], 4, v[4:5]
	v_or_b32_e32 v4, v4, v192
	v_lshl_add_u64 v[78:79], s[74:75], 0, v[4:5]
	v_mad_i64_i32 v[4:5], s[16:17], v64, s15, 0
	v_or3_b32 v4, v4, v66, v95
	v_lshl_add_u64 v[80:81], s[20:21], 0, v[4:5]
	v_mad_i64_i32 v[4:5], s[16:17], v64, s14, 0
	v_or3_b32 v4, v4, v66, v95
	v_lshl_add_u64 v[82:83], s[22:23], 0, v[4:5]
	v_lshlrev_b64 v[4:5], 10, v[64:65]
	v_or3_b32 v4, v4, v66, v95
	v_lshl_add_u64 v[84:85], s[74:75], 0, v[4:5]
	v_lshlrev_b64 v[4:5], 4, v[64:65]
	v_lshlrev_b32_e32 v2, 7, v94
	s_ashr_i32 s37, s36, 31
	v_or3_b32 v6, v6, v66, v95
	v_or_b32_e32 v4, v4, v192
	s_lshl_b32 s3, s56, 4
	s_mul_i32 s40, s56, 0x28000
	s_mul_hi_i32 s41, s36, 0x1400
	s_mul_i32 s42, s56, 0x118000
	s_mul_hi_i32 s43, s36, 0x8c00
	v_lshl_add_u64 v[76:77], s[74:75], 0, v[6:7]
	s_lshl_b64 s[44:45], s[36:37], 10
	s_lshl_b64 s[46:47], s[36:37], 4
	v_lshl_add_u64 v[86:87], s[74:75], 0, v[4:5]
	s_mov_b64 s[48:49], 0
	v_lshlrev_b32_e32 v192, 1, v2
	v_lshlrev_b32_e32 v88, 1, v0
	s_movk_i32 s19, 0x5000
	s_movk_i32 s20, 0x3fff
	s_mov_b64 s[22:23], 0x4000
	s_mov_b64 s[24:25], 0x8000

; __global__ void __launch_bounds__(512) mega(Args a) {
;     ...
;         int tok0 = gw;
;         for (; tok0 + 3 * NGW < MT; tok0 += 4 * NGW) {
;           const MixIn m0 = mix_load(tok0), m1 = mix_load(tok0 + NGW), m2 = mix_load(tok0 + 2 * NGW), m3 = mix_load(tok0 + 3 * NGW);
;           mix_item(tok0, m0); mix_item(tok0 + NGW, m1); mix_item(tok0 + 2 * NGW, m2); mix_item(tok0 + 3 * NGW, m3);
;         }
;         for (; tok0 < MT; tok0 += NGW) mix_item(tok0, mix_load(tok0));
.LBB0_192:
	s_or_b64 exec, exec, s[30:31]
	s_movk_i32 s2, 0x4000
	v_cmp_gt_i32_e32 vcc, s2, v64
	v_readlane_b32 s2, v250, 29
	s_cmp_eq_u32 s2, 2
	s_cbranch_scc0 .Lmx_b
	s_mov_b64 vcc, 0
.Lmx_b:
	s_and_saveexec_b64 s[2:3], vcc
	s_movk_i32 s15, 0x3fff
	s_cbranch_execz .LBB0_195
	v_mad_i64_i32 v[0:1], s[16:17], v64, s69, 0
	v_readlane_b32 s16, v251, 0
	v_or3_b32 v0, v0, v66, v95
	v_readlane_b32 s17, v251, 1
	v_ashrrev_i32_e32 v65, 31, v64
	s_ashr_i32 s11, s10, 31
	v_lshl_add_u64 v[4:5], s[16:17], 0, v[0:1]
	v_mad_i64_i32 v[0:1], s[16:17], v64, s14, 0
	v_readlane_b32 s16, v251, 2
	v_or3_b32 v0, v0, v66, v95
	v_readlane_b32 s17, v251, 3
	s_mul_hi_i32 s31, s10, 0x1400
	s_mul_i32 s30, s10, 0x1400
	v_lshl_add_u64 v[6:7], s[16:17], 0, v[0:1]
	v_lshlrev_b64 v[0:1], 10, v[64:65]
	v_or3_b32 v0, v0, v66, v95
	v_lshl_add_u64 v[8:9], s[74:75], 0, v[0:1]
	v_lshlrev_b64 v[0:1], 4, v[64:65]
	v_lshl_or_b32 v0, v94, 2, v0
	s_mul_hi_i32 s37, s10, 0x8c00
	s_mul_i32 s36, s10, 0x8c00
	s_lshl_b64 s[40:41], s[10:11], 10
	v_lshl_add_u64 v[10:11], s[74:75], 0, v[0:1]
	s_lshl_b64 s[42:43], s[10:11], 4
	s_mov_b64 s[44:45], 0

; __global__ void __launch_bounds__(512) mega(Args a) {
;     ...
;         for (; tok0 < MT; tok0 += NGW) mix_item(tok0, mix_load(tok0));
;       }
;       for (int i = 0;; ++i) {
;         const int un = i * G + cu; if (un >= NB * 8 * 32) break;
;         const int h = un & 7, qb = (un >> 3) & 31, b = un >> 8;
;         __syncthreads();
;         att::Unit U{};
;         const size_t tq = (size_t)b * SEQ + qb * 256;
;         U.Q = QBc + ((size_t)(b * 8 + h) * SEQ + qb * 256) * 128; U.K = KBc + (size_t)(b * 2 + (h >> 2)) * SEQ * 128; U.V = VBc + (size_t)(b * 2 + (h >> 2)) * SEQ * 128;
.LBB0_195:
	s_or_b64 exec, exec, s[2:3]
	v_readlane_b32 s2, v250, 29
	s_cmp_eq_u32 s2, 1
	s_cbranch_scc0 .Lmx_c
	v_writelane_b32 v250, 0, 29
	s_branch .LBB0_217
.Lmx_c:
	s_cmpk_gt_i32 s57, 0x1ff
	s_cbranch_scc1 .LBB0_217
	s_add_u32 s17, s0, 0x42000000
	s_addc_u32 s25, s1, 0
	s_add_u32 s58, s0, 0x44000000
	s_addc_u32 s59, s1, 0
	s_add_u32 s60, s0, 0x44800000
	s_addc_u32 s61, s1, 0
	v_readlane_b32 s0, v251, 4
	s_add_u32 s10, s0, s28
	v_readlane_b32 s0, v251, 5
	s_addc_u32 s11, s0, 0
	s_mov_b32 s40, 0
	s_mov_b32 s28, s57
	s_mov_b32 s0, s57
	s_mov_b32 s62, 0
	v_writelane_b32 v250, s4, 16
	v_writelane_b32 v250, s5, 17
	v_writelane_b32 v250, s6, 18
	v_writelane_b32 v250, s7, 19
	v_writelane_b32 v250, s66, 20
	v_writelane_b32 v250, s67, 21
	s_branch .LBB0_198

; __device__ __forceinline__ int opaque_v(int v) { asm volatile("" : "+v"(v)); return v; }
; __global__ void __launch_bounds__(512) mega(Args a) {
;     ...
;       for (int i = 0;; ++i) {
;         const int un = i * G + cu; if (un >= NB * 8 * 32) break;
;         const int h = un & 7, qb = (un >> 3) & 31, b = un >> 8;
;         __syncthreads();
;         att::Unit U{};
;         const size_t tq = (size_t)b * SEQ + qb * 256;
;         U.Q = QBc + ((size_t)(b * 8 + h) * SEQ + qb * 256) * 128; U.K = KBc + (size_t)(b * 2 + (h >> 2)) * SEQ * 128; U.V = VBc + (size_t)(b * 2 + (h >> 2)) * SEQ * 128;
;         U.ldq = 128; U.ldk = 128; U.NT = SEQ / 64;
;         U.O = Y + tq * YW + 1024 + h * 128; U.ldo = YW; U.Z = PROJ + tq * NIN + C_ZB + h * 128; U.ldz = NIN;
;         att::attn_body<0, 2, false>(U, shm, opaque_v(tid));
;       }
.LBB0_217:
	v_readlane_b32 s0, v250, 29
	s_cmp_eq_u32 s0, 2
	s_cbranch_scc0 .Lmx_d
	v_writelane_b32 v250, 1, 29
	s_branch .LBB0_188
